# prep row-norm loop: all 16 row loads of an item in flight behind one wait (on top of the gating readlane rewrite)
# speedup vs baseline: 1.0085x; 1.0009x over previous
; __device__ __forceinline__ float bflo(unsigned w) { return __uint_as_float(w << 16); }
; __device__ __forceinline__ float bfhi(unsigned w) { return __uint_as_float(w & 0xffff0000u); }
; __device__ __forceinline__ void prep_phase(const Args& a, LAS unsigned char* lds, int tid, int lane, int wave) {
;     ...
;     for (int wv = BID * NWAVES + wave; wv < Bn * 8 * (S / 64); wv += nwv) {
;         const int bh = wv / (S / 64), t = (wv % (S / 64)) * 64 + lane; const int b = bh >> 3, h = 8 + (bh & 7);
;         const v4u* qp = (const v4u*)(Q + ((size_t)(b * S + t)) * D + h * 64); const v4u* kp = (const v4u*)(Q + (size_t)32 * MiB + ((size_t)(b * S + t)) * D + h * 64);
;         float qs = 0.f, ks = 0.f;
; #pragma unroll
;         for (int c = 0; c < 8; ++c) { const v4u w = qp[c], x = kp[c];
;             qs += (bflo(w.x) * bflo(w.x) + bfhi(w.x) * bfhi(w.x)) + (bflo(w.y) * bflo(w.y) + bfhi(w.y) * bfhi(w.y)) + (bflo(w.z) * bflo(w.z) + bfhi(w.z) * bfhi(w.z)) + (bflo(w.w) * bflo(w.w) + bfhi(w.w) * bfhi(w.w));
;             ks += (bflo(x.x) * bflo(x.x) + bfhi(x.x) * bfhi(x.x)) + (bflo(x.y) * bflo(x.y) + bfhi(x.y) * bfhi(x.y)) + (bflo(x.z) * bflo(x.z) + bfhi(x.z) * bfhi(x.z)) + (bflo(x.w) * bflo(x.w) + bfhi(x.w) * bfhi(x.w)); }
.LBB0_548:
	s_ashr_i32 s8, s19, 31
	s_lshr_b32 s8, s8, 25
	s_add_i32 s8, s19, s8
	s_and_b32 s9, s8, 0x3ffff80
	s_ashr_i32 s22, s8, 7
	s_sub_i32 s9, s19, s9
	v_lshl_or_b32 v0, s9, 6, v12
	s_lshl_b32 s9, s22, 10
	s_and_b32 s9, s9, 0xffffe000
	v_add_u32_e32 v0, s9, v0
	s_waitcnt lgkmcnt(0)
	v_ashrrev_i32_e32 v1, 31, v0
	v_lshlrev_b64 v[0:1], 11, v[0:1]
	v_lshl_add_u64 v[2:3], s[4:5], 0, v[0:1]
	s_and_b32 s12, s8, 0x380
	v_lshl_add_u64 v[14:15], v[2:3], 0, s[12:13]
	global_load_dwordx4 v[24:27], v[14:15], off offset:1024
	v_lshl_add_u64 v[0:1], s[10:11], 0, v[0:1]
	v_lshl_add_u64 v[16:17], v[0:1], 0, s[12:13]
	global_load_dwordx4 v[28:31], v[16:17], off offset:1024
	global_load_dwordx4 v[32:35], v[14:15], off offset:1040
	global_load_dwordx4 v[36:39], v[16:17], off offset:1040
	global_load_dwordx4 v[4:7], v[14:15], off offset:1072
	global_load_dwordx4 v[40:43], v[14:15], off offset:1056
	global_load_dwordx4 v[0:3], v[16:17], off offset:1072
	global_load_dwordx4 v[8:11], v[16:17], off offset:1056
	global_load_dwordx4 v[176:179], v[14:15], off offset:1104
	global_load_dwordx4 v[180:183], v[14:15], off offset:1088
	global_load_dwordx4 v[184:187], v[16:17], off offset:1104
	global_load_dwordx4 v[188:191], v[16:17], off offset:1088
	global_load_dwordx4 v[192:195], v[14:15], off offset:1136
	global_load_dwordx4 v[196:199], v[14:15], off offset:1120
	global_load_dwordx4 v[200:203], v[16:17], off offset:1136
	global_load_dwordx4 v[204:207], v[16:17], off offset:1120
	s_waitcnt vmcnt(0)
	v_lshlrev_b32_e32 v48, 16, v28
	v_and_b32_e32 v28, 0xffff0000, v28
	v_lshlrev_b32_e32 v49, 16, v29
	v_lshlrev_b32_e32 v44, 16, v24
	v_and_b32_e32 v24, 0xffff0000, v24
	v_lshlrev_b32_e32 v45, 16, v25
	v_and_b32_e32 v25, 0xffff0000, v25
	v_and_b32_e32 v29, 0xffff0000, v29
	v_lshlrev_b32_e32 v52, 16, v32
	v_and_b32_e32 v32, 0xffff0000, v32
	v_lshlrev_b32_e32 v53, 16, v33
	v_and_b32_e32 v33, 0xffff0000, v33
	v_lshlrev_b32_e32 v46, 16, v26
	v_and_b32_e32 v26, 0xffff0000, v26
	v_lshlrev_b32_e32 v54, 16, v34
	v_and_b32_e32 v34, 0xffff0000, v34
	v_mul_f32_e32 v24, v24, v24
	v_mul_f32_e32 v25, v25, v25
	v_mul_f32_e32 v28, v28, v28
	v_mul_f32_e32 v29, v29, v29
	v_mul_f32_e32 v32, v32, v32
	v_mul_f32_e32 v33, v33, v33
	v_lshlrev_b32_e32 v47, 16, v27
	v_and_b32_e32 v27, 0xffff0000, v27
	v_lshlrev_b32_e32 v55, 16, v35
	v_and_b32_e32 v35, 0xffff0000, v35
	v_mul_f32_e32 v26, v26, v26
	v_mul_f32_e32 v34, v34, v34
	v_fmac_f32_e32 v24, v44, v44
	v_fmac_f32_e32 v25, v45, v45
	v_fmac_f32_e32 v28, v48, v48
	v_fmac_f32_e32 v29, v49, v49
	v_fmac_f32_e32 v32, v52, v52
	v_fmac_f32_e32 v33, v53, v53
	v_mul_f32_e32 v27, v27, v27
	v_mul_f32_e32 v35, v35, v35
	v_fmac_f32_e32 v26, v46, v46
	v_fmac_f32_e32 v34, v54, v54
	v_add_f32_e32 v24, v24, v25
	v_add_f32_e32 v25, v28, v29
	v_add_f32_e32 v28, v32, v33
	v_lshlrev_b32_e32 v56, 16, v36
	v_and_b32_e32 v36, 0xffff0000, v36
	v_lshlrev_b32_e32 v57, 16, v37
	v_and_b32_e32 v37, 0xffff0000, v37
	v_fmac_f32_e32 v27, v47, v47
	v_fmac_f32_e32 v35, v55, v55
	v_add_f32_e32 v24, v26, v24
	v_add_f32_e32 v26, v34, v28
	v_lshlrev_b32_e32 v50, 16, v30
	v_and_b32_e32 v30, 0xffff0000, v30
	v_lshlrev_b32_e32 v58, 16, v38
	v_and_b32_e32 v38, 0xffff0000, v38
	v_mul_f32_e32 v36, v36, v36
	v_mul_f32_e32 v37, v37, v37
	v_add_f32_e32 v24, v27, v24
	v_add_f32_e32 v26, v35, v26
	v_lshlrev_b32_e32 v51, 16, v31
	v_and_b32_e32 v31, 0xffff0000, v31
	v_mul_f32_e32 v30, v30, v30
	v_mul_f32_e32 v38, v38, v38
	v_fmac_f32_e32 v36, v56, v56
	v_fmac_f32_e32 v37, v57, v57
	v_add_f32_e32 v32, v24, v26
	v_and_b32_e32 v24, 0xffff0000, v39
	v_lshlrev_b32_e32 v59, 16, v39
	v_mul_f32_e32 v31, v31, v31
	v_fmac_f32_e32 v30, v50, v50
	v_fmac_f32_e32 v38, v58, v58
	v_add_f32_e32 v29, v36, v37
	v_mul_f32_e32 v24, v24, v24
	v_fmac_f32_e32 v31, v51, v51
	v_add_f32_e32 v25, v30, v25
	v_add_f32_e32 v28, v38, v29
	v_fmac_f32_e32 v24, v59, v59
	v_add_f32_e32 v25, v31, v25
	v_add_f32_e32 v24, v24, v28
	v_add_f32_e32 v44, v25, v24
	v_and_b32_e32 v25, 0xffff0000, v40
	v_lshlrev_b32_e32 v24, 16, v40
	v_mul_f32_e32 v33, v25, v25
	v_fmac_f32_e32 v33, v24, v24
	v_and_b32_e32 v24, 0xffff0000, v41
	v_lshlrev_b32_e32 v34, 16, v41
	v_mul_f32_e32 v35, v24, v24
	v_mov_b32_e32 v24, v176
	v_mov_b32_e32 v25, v177
	v_mov_b32_e32 v26, v178
	v_mov_b32_e32 v27, v179
	v_mov_b32_e32 v28, v180
	v_mov_b32_e32 v29, v181
	v_mov_b32_e32 v30, v182
	v_mov_b32_e32 v31, v183
	v_fmac_f32_e32 v35, v34, v34
	v_add_f32_e32 v33, v33, v35
	v_and_b32_e32 v35, 0xffff0000, v42
	v_lshlrev_b32_e32 v34, 16, v42
	v_mul_f32_e32 v35, v35, v35
	v_fmac_f32_e32 v35, v34, v34
	v_add_f32_e32 v33, v35, v33
	v_and_b32_e32 v35, 0xffff0000, v43
	v_lshlrev_b32_e32 v34, 16, v43
	v_mul_f32_e32 v35, v35, v35
	v_fmac_f32_e32 v35, v34, v34
	v_add_f32_e32 v33, v35, v33
	v_add_f32_e32 v40, v32, v33
	v_lshlrev_b32_e32 v32, 16, v8
	v_and_b32_e32 v8, 0xffff0000, v8
	v_mul_f32_e32 v8, v8, v8
	v_lshlrev_b32_e32 v41, 16, v9
	v_and_b32_e32 v9, 0xffff0000, v9
	v_fmac_f32_e32 v8, v32, v32
	v_mov_b32_e32 v32, v184
	v_mov_b32_e32 v33, v185
	v_mov_b32_e32 v34, v186
	v_mov_b32_e32 v35, v187
	v_mov_b32_e32 v36, v188
	v_mov_b32_e32 v37, v189
	v_mov_b32_e32 v38, v190
	v_mov_b32_e32 v39, v191
	v_mul_f32_e32 v9, v9, v9
	v_fmac_f32_e32 v9, v41, v41
	v_add_f32_e32 v8, v8, v9
	v_lshlrev_b32_e32 v9, 16, v10
	v_and_b32_e32 v10, 0xffff0000, v10
	v_mul_f32_e32 v10, v10, v10
	v_fmac_f32_e32 v10, v9, v9
	v_add_f32_e32 v8, v10, v8
	v_and_b32_e32 v10, 0xffff0000, v11
	v_lshlrev_b32_e32 v9, 16, v11
	v_mul_f32_e32 v10, v10, v10
	v_fmac_f32_e32 v10, v9, v9
	v_lshlrev_b32_e32 v9, 16, v4
	v_and_b32_e32 v4, 0xffff0000, v4
	v_mul_f32_e32 v4, v4, v4
	v_fmac_f32_e32 v4, v9, v9
	v_lshlrev_b32_e32 v9, 16, v5
; __device__ __forceinline__ float bflo(unsigned w) { return __uint_as_float(w << 16); }
; __device__ __forceinline__ float bfhi(unsigned w) { return __uint_as_float(w & 0xffff0000u); }
; __device__ __forceinline__ void prep_phase(const Args& a, LAS unsigned char* lds, int tid, int lane, int wave) {
;     ...
;         for (int c = 0; c < 8; ++c) { const v4u w = qp[c], x = kp[c];
;             qs += (bflo(w.x) * bflo(w.x) + bfhi(w.x) * bfhi(w.x)) + (bflo(w.y) * bflo(w.y) + bfhi(w.y) * bfhi(w.y)) + (bflo(w.z) * bflo(w.z) + bfhi(w.z) * bfhi(w.z)) + (bflo(w.w) * bflo(w.w) + bfhi(w.w) * bfhi(w.w));
;             ks += (bflo(x.x) * bflo(x.x) + bfhi(x.x) * bfhi(x.x)) + (bflo(x.y) * bflo(x.y) + bfhi(x.y) * bfhi(x.y)) + (bflo(x.z) * bflo(x.z) + bfhi(x.z) * bfhi(x.z)) + (bflo(x.w) * bflo(x.w) + bfhi(x.w) * bfhi(x.w)); }
	v_and_b32_e32 v5, 0xffff0000, v5
	v_mul_f32_e32 v5, v5, v5
	v_fmac_f32_e32 v5, v9, v9
	v_add_f32_e32 v4, v4, v5
	v_lshlrev_b32_e32 v5, 16, v6
	v_and_b32_e32 v6, 0xffff0000, v6
	v_mul_f32_e32 v6, v6, v6
	v_fmac_f32_e32 v6, v5, v5
	v_add_f32_e32 v4, v6, v4
	v_and_b32_e32 v6, 0xffff0000, v7
	v_lshlrev_b32_e32 v5, 16, v7
	v_mul_f32_e32 v6, v6, v6
	v_fmac_f32_e32 v6, v5, v5
	v_add_f32_e32 v4, v6, v4
	v_add_f32_e32 v40, v40, v4
	v_lshlrev_b32_e32 v4, 16, v0
	v_and_b32_e32 v0, 0xffff0000, v0
	v_mul_f32_e32 v0, v0, v0
	v_fmac_f32_e32 v0, v4, v4
	v_lshlrev_b32_e32 v4, 16, v1
	v_and_b32_e32 v1, 0xffff0000, v1
	v_mul_f32_e32 v1, v1, v1
	v_fmac_f32_e32 v1, v4, v4
	v_add_f32_e32 v0, v0, v1
	v_lshlrev_b32_e32 v1, 16, v2
	v_and_b32_e32 v2, 0xffff0000, v2
	v_mul_f32_e32 v2, v2, v2
	v_fmac_f32_e32 v2, v1, v1
	v_add_f32_e32 v0, v2, v0
	v_and_b32_e32 v2, 0xffff0000, v3
	v_lshlrev_b32_e32 v1, 16, v3
	v_mul_f32_e32 v2, v2, v2
	v_add_f32_e32 v8, v10, v8
	v_fmac_f32_e32 v2, v1, v1
	v_add_f32_e32 v8, v44, v8
	v_add_f32_e32 v0, v2, v0
	v_add_f32_e32 v41, v8, v0
	v_mov_b32_e32 v0, v192
	v_mov_b32_e32 v1, v193
	v_mov_b32_e32 v2, v194
	v_mov_b32_e32 v3, v195
	v_mov_b32_e32 v4, v196
	v_mov_b32_e32 v5, v197
	v_mov_b32_e32 v6, v198
	v_mov_b32_e32 v7, v199
	v_mov_b32_e32 v8, v200
	v_mov_b32_e32 v9, v201
	v_mov_b32_e32 v10, v202
	v_mov_b32_e32 v11, v203
	s_nop 0
	v_mov_b32_e32 v14, v204
	v_mov_b32_e32 v15, v205
	v_mov_b32_e32 v16, v206
	v_mov_b32_e32 v17, v207
	s_waitcnt vmcnt(6)
	v_lshlrev_b32_e32 v42, 16, v28
	v_and_b32_e32 v28, 0xffff0000, v28
	v_mul_f32_e32 v28, v28, v28
	v_fmac_f32_e32 v28, v42, v42
	v_lshlrev_b32_e32 v42, 16, v29
	v_and_b32_e32 v29, 0xffff0000, v29
	v_mul_f32_e32 v29, v29, v29
	v_fmac_f32_e32 v29, v42, v42
	v_add_f32_e32 v28, v28, v29
	v_lshlrev_b32_e32 v29, 16, v30
	v_and_b32_e32 v30, 0xffff0000, v30
	v_mul_f32_e32 v30, v30, v30
	v_fmac_f32_e32 v30, v29, v29
	v_add_f32_e32 v28, v30, v28
	v_and_b32_e32 v30, 0xffff0000, v31
	v_lshlrev_b32_e32 v29, 16, v31
	v_mul_f32_e32 v30, v30, v30
	v_fmac_f32_e32 v30, v29, v29
	v_add_f32_e32 v28, v30, v28
	v_add_f32_e32 v28, v40, v28
	s_waitcnt vmcnt(4)
	v_and_b32_e32 v30, 0xffff0000, v36
	v_lshlrev_b32_e32 v29, 16, v36
	v_mul_f32_e32 v30, v30, v30
	v_and_b32_e32 v31, 0xffff0000, v37
	v_fmac_f32_e32 v30, v29, v29
	v_lshlrev_b32_e32 v29, 16, v37
	v_mul_f32_e32 v31, v31, v31
	v_fmac_f32_e32 v31, v29, v29
	v_add_f32_e32 v29, v30, v31
	v_and_b32_e32 v31, 0xffff0000, v38
	v_lshlrev_b32_e32 v30, 16, v38
	v_mul_f32_e32 v31, v31, v31
	v_fmac_f32_e32 v31, v30, v30
	v_add_f32_e32 v29, v31, v29
	v_and_b32_e32 v31, 0xffff0000, v39
	v_lshlrev_b32_e32 v30, 16, v39
	v_mul_f32_e32 v31, v31, v31
	v_fmac_f32_e32 v31, v30, v30
	v_lshlrev_b32_e32 v30, 16, v24
	v_and_b32_e32 v24, 0xffff0000, v24
	v_mul_f32_e32 v24, v24, v24
	v_fmac_f32_e32 v24, v30, v30
	v_lshlrev_b32_e32 v30, 16, v25
	v_and_b32_e32 v25, 0xffff0000, v25
	v_mul_f32_e32 v25, v25, v25
	v_fmac_f32_e32 v25, v30, v30
	v_add_f32_e32 v24, v24, v25
	v_lshlrev_b32_e32 v25, 16, v26
	v_and_b32_e32 v26, 0xffff0000, v26
	v_mul_f32_e32 v26, v26, v26
	v_fmac_f32_e32 v26, v25, v25
	v_add_f32_e32 v24, v26, v24
	v_and_b32_e32 v26, 0xffff0000, v27
	v_lshlrev_b32_e32 v25, 16, v27
	v_mul_f32_e32 v26, v26, v26
	v_fmac_f32_e32 v26, v25, v25
	v_add_f32_e32 v24, v26, v24
	v_and_b32_e32 v26, 0xffff0000, v32
	v_lshlrev_b32_e32 v25, 16, v32
	v_mul_f32_e32 v26, v26, v26
	v_and_b32_e32 v27, 0xffff0000, v33
	v_fmac_f32_e32 v26, v25, v25
	v_lshlrev_b32_e32 v25, 16, v33
	v_mul_f32_e32 v27, v27, v27
	v_fmac_f32_e32 v27, v25, v25
	v_add_f32_e32 v25, v26, v27
	v_and_b32_e32 v27, 0xffff0000, v34
	v_lshlrev_b32_e32 v26, 16, v34
	v_mul_f32_e32 v27, v27, v27
	v_fmac_f32_e32 v27, v26, v26
	v_add_f32_e32 v25, v27, v25
	v_and_b32_e32 v27, 0xffff0000, v35
	v_lshlrev_b32_e32 v26, 16, v35
	v_mul_f32_e32 v27, v27, v27
	v_fmac_f32_e32 v27, v26, v26
	s_waitcnt vmcnt(2)
; __device__ __forceinline__ float bflo(unsigned w) { return __uint_as_float(w << 16); }
; __device__ __forceinline__ float bfhi(unsigned w) { return __uint_as_float(w & 0xffff0000u); }
; __device__ __forceinline__ void prep_phase(const Args& a, LAS unsigned char* lds, int tid, int lane, int wave) {
;     ...
;         for (int c = 0; c < 8; ++c) { const v4u w = qp[c], x = kp[c];
;             qs += (bflo(w.x) * bflo(w.x) + bfhi(w.x) * bfhi(w.x)) + (bflo(w.y) * bflo(w.y) + bfhi(w.y) * bfhi(w.y)) + (bflo(w.z) * bflo(w.z) + bfhi(w.z) * bfhi(w.z)) + (bflo(w.w) * bflo(w.w) + bfhi(w.w) * bfhi(w.w));
;             ks += (bflo(x.x) * bflo(x.x) + bfhi(x.x) * bfhi(x.x)) + (bflo(x.y) * bflo(x.y) + bfhi(x.y) * bfhi(x.y)) + (bflo(x.z) * bflo(x.z) + bfhi(x.z) * bfhi(x.z)) + (bflo(x.w) * bflo(x.w) + bfhi(x.w) * bfhi(x.w)); }
; #pragma unroll
;         for (int o = 1; o < 64; o <<= 1) { qs = fmaxf(qs, __shfl_xor(qs, o)); ks = fmaxf(ks, __shfl_xor(ks, o)); }
;         if (lane == 0) { atomicMax((unsigned*)ws + 3700 + bh, __float_as_uint(qs)); atomicMax((unsigned*)ws + 3732 + bh, __float_as_uint(ks)); }
	v_lshlrev_b32_e32 v26, 16, v4
	v_and_b32_e32 v4, 0xffff0000, v4
	v_mul_f32_e32 v4, v4, v4
	v_fmac_f32_e32 v4, v26, v26
	v_lshlrev_b32_e32 v26, 16, v5
	v_and_b32_e32 v5, 0xffff0000, v5
	v_mul_f32_e32 v5, v5, v5
	v_fmac_f32_e32 v5, v26, v26
	v_add_f32_e32 v4, v4, v5
	v_lshlrev_b32_e32 v5, 16, v6
	v_and_b32_e32 v6, 0xffff0000, v6
	v_mul_f32_e32 v6, v6, v6
	v_fmac_f32_e32 v6, v5, v5
	v_add_f32_e32 v4, v6, v4
	v_and_b32_e32 v6, 0xffff0000, v7
	v_lshlrev_b32_e32 v5, 16, v7
	v_mul_f32_e32 v6, v6, v6
	v_fmac_f32_e32 v6, v5, v5
	v_add_f32_e32 v4, v6, v4
	s_waitcnt vmcnt(0)
	v_and_b32_e32 v6, 0xffff0000, v14
	v_lshlrev_b32_e32 v5, 16, v14
	v_mul_f32_e32 v6, v6, v6
	v_and_b32_e32 v7, 0xffff0000, v15
	v_fmac_f32_e32 v6, v5, v5
	v_lshlrev_b32_e32 v5, 16, v15
	v_mul_f32_e32 v7, v7, v7
	v_fmac_f32_e32 v7, v5, v5
	v_add_f32_e32 v5, v6, v7
	v_and_b32_e32 v7, 0xffff0000, v16
	v_lshlrev_b32_e32 v6, 16, v16
	v_mul_f32_e32 v7, v7, v7
	v_fmac_f32_e32 v7, v6, v6
	v_add_f32_e32 v5, v7, v5
	v_and_b32_e32 v7, 0xffff0000, v17
	v_lshlrev_b32_e32 v6, 16, v17
	v_mul_f32_e32 v7, v7, v7
	v_fmac_f32_e32 v7, v6, v6
	v_lshlrev_b32_e32 v6, 16, v0
	v_and_b32_e32 v0, 0xffff0000, v0
	v_mul_f32_e32 v0, v0, v0
	v_fmac_f32_e32 v0, v6, v6
	v_lshlrev_b32_e32 v6, 16, v1
	v_and_b32_e32 v1, 0xffff0000, v1
	v_mul_f32_e32 v1, v1, v1
	v_fmac_f32_e32 v1, v6, v6
	v_add_f32_e32 v0, v0, v1
	v_lshlrev_b32_e32 v1, 16, v2
	v_and_b32_e32 v2, 0xffff0000, v2
	v_mul_f32_e32 v2, v2, v2
	v_fmac_f32_e32 v2, v1, v1
	v_add_f32_e32 v0, v2, v0
	v_and_b32_e32 v2, 0xffff0000, v3
	v_lshlrev_b32_e32 v1, 16, v3
	v_mul_f32_e32 v2, v2, v2
	v_fmac_f32_e32 v2, v1, v1
	v_add_f32_e32 v0, v2, v0
	v_and_b32_e32 v2, 0xffff0000, v8
	v_lshlrev_b32_e32 v1, 16, v8
	v_mul_f32_e32 v2, v2, v2
	v_and_b32_e32 v3, 0xffff0000, v9
	v_fmac_f32_e32 v2, v1, v1
	v_lshlrev_b32_e32 v1, 16, v9
	v_mul_f32_e32 v3, v3, v3
	v_fmac_f32_e32 v3, v1, v1
	v_add_f32_e32 v1, v2, v3
	v_and_b32_e32 v3, 0xffff0000, v10
	v_lshlrev_b32_e32 v2, 16, v10
	v_mul_f32_e32 v3, v3, v3
	v_fmac_f32_e32 v3, v2, v2
	v_add_f32_e32 v29, v31, v29
	v_add_f32_e32 v1, v3, v1
	v_and_b32_e32 v3, 0xffff0000, v11
	v_add_f32_e32 v29, v41, v29
	v_add_f32_e32 v24, v28, v24
	v_add_f32_e32 v25, v27, v25
	v_lshlrev_b32_e32 v2, 16, v11
	v_mul_f32_e32 v3, v3, v3
	v_add_f32_e32 v25, v29, v25
	v_add_f32_e32 v4, v24, v4
	v_add_f32_e32 v5, v7, v5
	v_fmac_f32_e32 v3, v2, v2
	v_add_f32_e32 v5, v25, v5
	v_add_f32_e32 v0, v4, v0
	v_add_f32_e32 v1, v3, v1
	ds_bpermute_b32 v2, v13, v0
	v_add_f32_e32 v1, v5, v1
	ds_bpermute_b32 v3, v13, v1
	s_waitcnt lgkmcnt(1)
	v_max_f32_e32 v2, v2, v2
	v_max_f32_e32 v0, v0, v2
	s_waitcnt lgkmcnt(0)
	v_max_f32_e32 v2, v3, v3
	ds_bpermute_b32 v3, v18, v0
	v_max_f32_e32 v1, v1, v2
	ds_bpermute_b32 v2, v18, v1
	s_waitcnt lgkmcnt(1)
	v_max_f32_e32 v3, v3, v3
	v_max_f32_e32 v0, v0, v3
	s_waitcnt lgkmcnt(0)
	v_max_f32_e32 v2, v2, v2
	ds_bpermute_b32 v3, v19, v0
	v_max_f32_e32 v1, v1, v2
	ds_bpermute_b32 v2, v19, v1
	s_waitcnt lgkmcnt(1)
	v_max_f32_e32 v3, v3, v3
	v_max_f32_e32 v0, v0, v3
	s_waitcnt lgkmcnt(0)
	v_max_f32_e32 v2, v2, v2
	ds_bpermute_b32 v3, v20, v0
	v_max_f32_e32 v1, v1, v2
	ds_bpermute_b32 v2, v20, v1
	s_waitcnt lgkmcnt(1)
	v_max_f32_e32 v3, v3, v3
	v_max_f32_e32 v0, v0, v3
	s_waitcnt lgkmcnt(0)
	v_max_f32_e32 v2, v2, v2
	ds_bpermute_b32 v3, v21, v0
	v_max_f32_e32 v1, v1, v2
	ds_bpermute_b32 v4, v21, v1
	s_waitcnt lgkmcnt(1)
	v_max_f32_e32 v2, v3, v3
	v_max_f32_e32 v2, v0, v2
	s_waitcnt lgkmcnt(0)
	v_max_f32_e32 v0, v4, v4
	v_max_f32_e32 v0, v1, v0
	ds_bpermute_b32 v3, v22, v2
	ds_bpermute_b32 v1, v22, v0
	s_and_saveexec_b64 s[24:25], vcc
	s_cbranch_execz .LBB0_547
	s_waitcnt lgkmcnt(1)
	v_max_f32_e32 v3, v3, v3
	v_max_f32_e32 v2, v2, v2
	s_mov_b64 s[26:27], exec
	v_max_f32_e32 v2, v2, v3
	s_mov_b32 s12, 0
